# P2 gelu tiles: epilogue arithmetic re-issued as packed f32 ops (same per-element operations), one row-pointer register pair
# speedup vs baseline: 1.0024x; 1.0024x over previous
; __device__ __forceinline__ unsigned cvt_pk_bf16(float lo, float hi) { unsigned r; asm volatile("v_cvt_pk_bf16_f32 %0, %1, %2" : "=v"(r) : "v"(lo), "v"(hi)); return r; }
; __device__ __forceinline__ float gelu_tanh(float x) {
;     const float t = x * (1.0f + 0.044715f * x * x);
;     const float e = __builtin_amdgcn_exp2f(-2.0f * 0.7978845608028654f * 1.4426950408889634f * t);
;     return x * __builtin_amdgcn_rcpf(1.0f + e);
; }
;     __device__ __forceinline__ void operator()(const f32x4 (&acc)[2][2][4][2], const Unit& u, int wr, int wc, int fr, int fq) const {
;     ...
;             const int col0 = u.pn * BM + wc * 32 + 8 * fq;
; #pragma unroll
;             for (int ai = 0; ai < 2; ++ai)
; #pragma unroll
;                 for (int m = 0; m < 4; ++m) { bf16_t* rowp = Zo + (size_t)(row0 + ai * HALF + m * 16) * NZ + col0;
; #pragma unroll
;                     for (int bj = 0; bj < 2; ++bj) { f32x4 v0 = acc[ai][bj][m][0], v1 = acc[ai][bj][m][1];
; #pragma unroll
;                         for (int e = 0; e < 4; ++e) { v0[e] = gelu_tanh(v0[e]); v1[e] = gelu_tanh(v1[e]); }
;                         u32x4 w; w.x = cvt_pk_bf16(v0[0], v0[1]); w.y = cvt_pk_bf16(v0[2], v0[3]); w.z = cvt_pk_bf16(v1[0], v1[1]); w.w = cvt_pk_bf16(v1[2], v1[3]);
;                         *(u32x4*)(rowp + bj * HALF) = w; } }
.LBB0_189:
	s_and_b64 vcc, exec, s[8:9]
	s_cbranch_vccz .LBB0_273
	v_mov_b32_e32 v240, 0x3d372713
	v_mov_b32_e32 v241, 0x3d372713
	v_mov_b32_e32 v242, 0xc0135761
	v_mov_b32_e32 v243, 0xc0135761
	v_mov_b32_e32 v244, 1.0
	v_mov_b32_e32 v245, 1.0
	v_lshl_add_u32 v160, s50, 8, v162
	v_mov_b64_e32 v[158:159], s[20:21]
	v_mad_i64_i32 v[250:251], s[8:9], v160, s69, v[158:159]
	v_lshl_or_b32 v136, s48, 9, v138
	v_lshl_add_u64 v[250:251], v[250:251], 0, v[136:137]
	v_pk_mul_f32 v[232:233], v[124:125], v[240:241]
	v_pk_mul_f32 v[234:235], v[126:127], v[240:241]
	v_pk_mul_f32 v[236:237], v[120:121], v[240:241]
	v_pk_mul_f32 v[238:239], v[122:123], v[240:241]
	v_pk_fma_f32 v[232:233], v[124:125], v[232:233], v[244:245]
	v_pk_fma_f32 v[234:235], v[126:127], v[234:235], v[244:245]
	v_pk_fma_f32 v[236:237], v[120:121], v[236:237], v[244:245]
	v_pk_fma_f32 v[238:239], v[122:123], v[238:239], v[244:245]
	v_pk_mul_f32 v[232:233], v[124:125], v[232:233]
	v_pk_mul_f32 v[234:235], v[126:127], v[234:235]
	v_pk_mul_f32 v[236:237], v[120:121], v[236:237]
	v_pk_mul_f32 v[238:239], v[122:123], v[238:239]
	v_pk_mul_f32 v[232:233], v[232:233], v[242:243]
	v_pk_mul_f32 v[234:235], v[234:235], v[242:243]
	v_pk_mul_f32 v[236:237], v[236:237], v[242:243]
	v_pk_mul_f32 v[238:239], v[238:239], v[242:243]
	v_exp_f32_e32 v232, v232
	v_exp_f32_e32 v233, v233
	v_exp_f32_e32 v234, v234
	v_exp_f32_e32 v235, v235
	v_exp_f32_e32 v236, v236
	v_exp_f32_e32 v237, v237
	v_exp_f32_e32 v238, v238
	v_exp_f32_e32 v239, v239
	v_pk_add_f32 v[232:233], v[232:233], v[244:245]
	v_pk_add_f32 v[234:235], v[234:235], v[244:245]
	v_pk_add_f32 v[236:237], v[236:237], v[244:245]
	v_pk_add_f32 v[238:239], v[238:239], v[244:245]
	v_rcp_f32_e32 v232, v232
	v_rcp_f32_e32 v233, v233
	v_rcp_f32_e32 v234, v234
	v_rcp_f32_e32 v235, v235
	v_rcp_f32_e32 v236, v236
	v_rcp_f32_e32 v237, v237
	v_rcp_f32_e32 v238, v238
	v_rcp_f32_e32 v239, v239
	v_pk_mul_f32 v[232:233], v[124:125], v[232:233]
	v_pk_mul_f32 v[234:235], v[126:127], v[234:235]
	v_pk_mul_f32 v[236:237], v[120:121], v[236:237]
	v_pk_mul_f32 v[238:239], v[122:123], v[238:239]
	v_cvt_pk_bf16_f32 v246, v232, v233
	v_cvt_pk_bf16_f32 v247, v234, v235
	v_cvt_pk_bf16_f32 v248, v236, v237
	v_cvt_pk_bf16_f32 v249, v238, v239
	global_store_dwordx4 v[250:251], v[246:249], off
	s_nop 1
	v_pk_mul_f32 v[232:233], v[116:117], v[240:241]
	v_pk_mul_f32 v[234:235], v[118:119], v[240:241]
	v_pk_mul_f32 v[236:237], v[112:113], v[240:241]
	v_pk_mul_f32 v[238:239], v[114:115], v[240:241]
	v_pk_fma_f32 v[232:233], v[116:117], v[232:233], v[244:245]
	v_pk_fma_f32 v[234:235], v[118:119], v[234:235], v[244:245]
	v_pk_fma_f32 v[236:237], v[112:113], v[236:237], v[244:245]
	v_pk_fma_f32 v[238:239], v[114:115], v[238:239], v[244:245]
	v_pk_mul_f32 v[232:233], v[116:117], v[232:233]
	v_pk_mul_f32 v[234:235], v[118:119], v[234:235]
	v_pk_mul_f32 v[236:237], v[112:113], v[236:237]
	v_pk_mul_f32 v[238:239], v[114:115], v[238:239]
	v_pk_mul_f32 v[232:233], v[232:233], v[242:243]
	v_pk_mul_f32 v[234:235], v[234:235], v[242:243]
	v_pk_mul_f32 v[236:237], v[236:237], v[242:243]
	v_pk_mul_f32 v[238:239], v[238:239], v[242:243]
	v_exp_f32_e32 v232, v232
	v_exp_f32_e32 v233, v233
	v_exp_f32_e32 v234, v234
	v_exp_f32_e32 v235, v235
	v_exp_f32_e32 v236, v236
	v_exp_f32_e32 v237, v237
	v_exp_f32_e32 v238, v238
	v_exp_f32_e32 v239, v239
	v_pk_add_f32 v[232:233], v[232:233], v[244:245]
	v_pk_add_f32 v[234:235], v[234:235], v[244:245]
	v_pk_add_f32 v[236:237], v[236:237], v[244:245]
	v_pk_add_f32 v[238:239], v[238:239], v[244:245]
	v_rcp_f32_e32 v232, v232
	v_rcp_f32_e32 v233, v233
	v_rcp_f32_e32 v234, v234
	v_rcp_f32_e32 v235, v235
	v_rcp_f32_e32 v236, v236
	v_rcp_f32_e32 v237, v237
	v_rcp_f32_e32 v238, v238
	v_rcp_f32_e32 v239, v239
	v_pk_mul_f32 v[232:233], v[116:117], v[232:233]
	v_pk_mul_f32 v[234:235], v[118:119], v[234:235]
	v_pk_mul_f32 v[236:237], v[112:113], v[236:237]
	v_pk_mul_f32 v[238:239], v[114:115], v[238:239]
	v_cvt_pk_bf16_f32 v246, v232, v233
	v_cvt_pk_bf16_f32 v247, v234, v235
	v_cvt_pk_bf16_f32 v248, v236, v237
	v_cvt_pk_bf16_f32 v249, v238, v239
	global_store_dwordx4 v[250:251], v[246:249], off offset:256
	v_or_b32_e32 v250, 16, v160
	v_mad_i64_i32 v[250:251], s[8:9], v250, s69, v[158:159]
	v_lshl_add_u64 v[250:251], v[250:251], 0, v[136:137]
	v_pk_mul_f32 v[232:233], v[108:109], v[240:241]
	v_pk_mul_f32 v[234:235], v[110:111], v[240:241]
	v_pk_mul_f32 v[236:237], v[104:105], v[240:241]
	v_pk_mul_f32 v[238:239], v[106:107], v[240:241]
	v_pk_fma_f32 v[232:233], v[108:109], v[232:233], v[244:245]
	v_pk_fma_f32 v[234:235], v[110:111], v[234:235], v[244:245]
	v_pk_fma_f32 v[236:237], v[104:105], v[236:237], v[244:245]
	v_pk_fma_f32 v[238:239], v[106:107], v[238:239], v[244:245]
	v_pk_mul_f32 v[232:233], v[108:109], v[232:233]
	v_pk_mul_f32 v[234:235], v[110:111], v[234:235]
	v_pk_mul_f32 v[236:237], v[104:105], v[236:237]
	v_pk_mul_f32 v[238:239], v[106:107], v[238:239]
	v_pk_mul_f32 v[232:233], v[232:233], v[242:243]
	v_pk_mul_f32 v[234:235], v[234:235], v[242:243]
	v_pk_mul_f32 v[236:237], v[236:237], v[242:243]
	v_pk_mul_f32 v[238:239], v[238:239], v[242:243]
	v_exp_f32_e32 v232, v232
	v_exp_f32_e32 v233, v233
	v_exp_f32_e32 v234, v234
	v_exp_f32_e32 v235, v235
	v_exp_f32_e32 v236, v236
	v_exp_f32_e32 v237, v237
	v_exp_f32_e32 v238, v238
	v_exp_f32_e32 v239, v239
	v_pk_add_f32 v[232:233], v[232:233], v[244:245]
	v_pk_add_f32 v[234:235], v[234:235], v[244:245]
	v_pk_add_f32 v[236:237], v[236:237], v[244:245]
	v_pk_add_f32 v[238:239], v[238:239], v[244:245]
	v_rcp_f32_e32 v232, v232
	v_rcp_f32_e32 v233, v233
	v_rcp_f32_e32 v234, v234
	v_rcp_f32_e32 v235, v235
; __device__ __forceinline__ unsigned cvt_pk_bf16(float lo, float hi) { unsigned r; asm volatile("v_cvt_pk_bf16_f32 %0, %1, %2" : "=v"(r) : "v"(lo), "v"(hi)); return r; }
; __device__ __forceinline__ float gelu_tanh(float x) {
;     const float t = x * (1.0f + 0.044715f * x * x);
;     const float e = __builtin_amdgcn_exp2f(-2.0f * 0.7978845608028654f * 1.4426950408889634f * t);
;     return x * __builtin_amdgcn_rcpf(1.0f + e);
; }
;     __device__ __forceinline__ void operator()(const f32x4 (&acc)[2][2][4][2], const Unit& u, int wr, int wc, int fr, int fq) const {
;     ...
;             const int col0 = u.pn * BM + wc * 32 + 8 * fq;
; #pragma unroll
;             for (int ai = 0; ai < 2; ++ai)
; #pragma unroll
;                 for (int m = 0; m < 4; ++m) { bf16_t* rowp = Zo + (size_t)(row0 + ai * HALF + m * 16) * NZ + col0;
; #pragma unroll
;                     for (int bj = 0; bj < 2; ++bj) { f32x4 v0 = acc[ai][bj][m][0], v1 = acc[ai][bj][m][1];
; #pragma unroll
;                         for (int e = 0; e < 4; ++e) { v0[e] = gelu_tanh(v0[e]); v1[e] = gelu_tanh(v1[e]); }
;                         u32x4 w; w.x = cvt_pk_bf16(v0[0], v0[1]); w.y = cvt_pk_bf16(v0[2], v0[3]); w.z = cvt_pk_bf16(v1[0], v1[1]); w.w = cvt_pk_bf16(v1[2], v1[3]);
;                         *(u32x4*)(rowp + bj * HALF) = w; } }
	v_rcp_f32_e32 v236, v236
	v_rcp_f32_e32 v237, v237
	v_rcp_f32_e32 v238, v238
	v_rcp_f32_e32 v239, v239
	v_pk_mul_f32 v[232:233], v[108:109], v[232:233]
	v_pk_mul_f32 v[234:235], v[110:111], v[234:235]
	v_pk_mul_f32 v[236:237], v[104:105], v[236:237]
	v_pk_mul_f32 v[238:239], v[106:107], v[238:239]
	v_cvt_pk_bf16_f32 v246, v232, v233
	v_cvt_pk_bf16_f32 v247, v234, v235
	v_cvt_pk_bf16_f32 v248, v236, v237
	v_cvt_pk_bf16_f32 v249, v238, v239
	global_store_dwordx4 v[250:251], v[246:249], off
	s_nop 1
	v_pk_mul_f32 v[232:233], v[100:101], v[240:241]
	v_pk_mul_f32 v[234:235], v[102:103], v[240:241]
	v_pk_mul_f32 v[236:237], v[96:97], v[240:241]
	v_pk_mul_f32 v[238:239], v[98:99], v[240:241]
	v_pk_fma_f32 v[232:233], v[100:101], v[232:233], v[244:245]
	v_pk_fma_f32 v[234:235], v[102:103], v[234:235], v[244:245]
	v_pk_fma_f32 v[236:237], v[96:97], v[236:237], v[244:245]
	v_pk_fma_f32 v[238:239], v[98:99], v[238:239], v[244:245]
	v_pk_mul_f32 v[232:233], v[100:101], v[232:233]
	v_pk_mul_f32 v[234:235], v[102:103], v[234:235]
	v_pk_mul_f32 v[236:237], v[96:97], v[236:237]
	v_pk_mul_f32 v[238:239], v[98:99], v[238:239]
	v_pk_mul_f32 v[232:233], v[232:233], v[242:243]
	v_pk_mul_f32 v[234:235], v[234:235], v[242:243]
	v_pk_mul_f32 v[236:237], v[236:237], v[242:243]
	v_pk_mul_f32 v[238:239], v[238:239], v[242:243]
	v_exp_f32_e32 v232, v232
	v_exp_f32_e32 v233, v233
	v_exp_f32_e32 v234, v234
	v_exp_f32_e32 v235, v235
	v_exp_f32_e32 v236, v236
	v_exp_f32_e32 v237, v237
	v_exp_f32_e32 v238, v238
	v_exp_f32_e32 v239, v239
	v_pk_add_f32 v[232:233], v[232:233], v[244:245]
	v_pk_add_f32 v[234:235], v[234:235], v[244:245]
	v_pk_add_f32 v[236:237], v[236:237], v[244:245]
	v_pk_add_f32 v[238:239], v[238:239], v[244:245]
	v_rcp_f32_e32 v232, v232
	v_rcp_f32_e32 v233, v233
	v_rcp_f32_e32 v234, v234
	v_rcp_f32_e32 v235, v235
	v_rcp_f32_e32 v236, v236
	v_rcp_f32_e32 v237, v237
	v_rcp_f32_e32 v238, v238
	v_rcp_f32_e32 v239, v239
	v_pk_mul_f32 v[232:233], v[100:101], v[232:233]
	v_pk_mul_f32 v[234:235], v[102:103], v[234:235]
	v_pk_mul_f32 v[236:237], v[96:97], v[236:237]
	v_pk_mul_f32 v[238:239], v[98:99], v[238:239]
	v_cvt_pk_bf16_f32 v246, v232, v233
	v_cvt_pk_bf16_f32 v247, v234, v235
	v_cvt_pk_bf16_f32 v248, v236, v237
	v_cvt_pk_bf16_f32 v249, v238, v239
	global_store_dwordx4 v[250:251], v[246:249], off offset:256
	v_or_b32_e32 v250, 32, v160
	v_mad_i64_i32 v[250:251], s[8:9], v250, s69, v[158:159]
	v_lshl_add_u64 v[250:251], v[250:251], 0, v[136:137]
	v_pk_mul_f32 v[232:233], v[92:93], v[240:241]
	v_pk_mul_f32 v[234:235], v[94:95], v[240:241]
	v_pk_mul_f32 v[236:237], v[88:89], v[240:241]
	v_pk_mul_f32 v[238:239], v[90:91], v[240:241]
	v_pk_fma_f32 v[232:233], v[92:93], v[232:233], v[244:245]
	v_pk_fma_f32 v[234:235], v[94:95], v[234:235], v[244:245]
	v_pk_fma_f32 v[236:237], v[88:89], v[236:237], v[244:245]
	v_pk_fma_f32 v[238:239], v[90:91], v[238:239], v[244:245]
	v_pk_mul_f32 v[232:233], v[92:93], v[232:233]
	v_pk_mul_f32 v[234:235], v[94:95], v[234:235]
	v_pk_mul_f32 v[236:237], v[88:89], v[236:237]
	v_pk_mul_f32 v[238:239], v[90:91], v[238:239]
	v_pk_mul_f32 v[232:233], v[232:233], v[242:243]
	v_pk_mul_f32 v[234:235], v[234:235], v[242:243]
	v_pk_mul_f32 v[236:237], v[236:237], v[242:243]
	v_pk_mul_f32 v[238:239], v[238:239], v[242:243]
	v_exp_f32_e32 v232, v232
	v_exp_f32_e32 v233, v233
	v_exp_f32_e32 v234, v234
	v_exp_f32_e32 v235, v235
	v_exp_f32_e32 v236, v236
	v_exp_f32_e32 v237, v237
	v_exp_f32_e32 v238, v238
	v_exp_f32_e32 v239, v239
	v_pk_add_f32 v[232:233], v[232:233], v[244:245]
	v_pk_add_f32 v[234:235], v[234:235], v[244:245]
	v_pk_add_f32 v[236:237], v[236:237], v[244:245]
	v_pk_add_f32 v[238:239], v[238:239], v[244:245]
	v_rcp_f32_e32 v232, v232
	v_rcp_f32_e32 v233, v233
	v_rcp_f32_e32 v234, v234
	v_rcp_f32_e32 v235, v235
	v_rcp_f32_e32 v236, v236
	v_rcp_f32_e32 v237, v237
	v_rcp_f32_e32 v238, v238
	v_rcp_f32_e32 v239, v239
	v_pk_mul_f32 v[232:233], v[92:93], v[232:233]
	v_pk_mul_f32 v[234:235], v[94:95], v[234:235]
	v_pk_mul_f32 v[236:237], v[88:89], v[236:237]
	v_pk_mul_f32 v[238:239], v[90:91], v[238:239]
	v_cvt_pk_bf16_f32 v246, v232, v233
	v_cvt_pk_bf16_f32 v247, v234, v235
	v_cvt_pk_bf16_f32 v248, v236, v237
	v_cvt_pk_bf16_f32 v249, v238, v239
	global_store_dwordx4 v[250:251], v[246:249], off
	s_nop 1
	v_pk_mul_f32 v[232:233], v[84:85], v[240:241]
	v_pk_mul_f32 v[234:235], v[86:87], v[240:241]
	v_pk_mul_f32 v[236:237], v[80:81], v[240:241]
	v_pk_mul_f32 v[238:239], v[82:83], v[240:241]
	v_pk_fma_f32 v[232:233], v[84:85], v[232:233], v[244:245]
	v_pk_fma_f32 v[234:235], v[86:87], v[234:235], v[244:245]
	v_pk_fma_f32 v[236:237], v[80:81], v[236:237], v[244:245]
	v_pk_fma_f32 v[238:239], v[82:83], v[238:239], v[244:245]
	v_pk_mul_f32 v[232:233], v[84:85], v[232:233]
	v_pk_mul_f32 v[234:235], v[86:87], v[234:235]
	v_pk_mul_f32 v[236:237], v[80:81], v[236:237]
	v_pk_mul_f32 v[238:239], v[82:83], v[238:239]
	v_pk_mul_f32 v[232:233], v[232:233], v[242:243]
	v_pk_mul_f32 v[234:235], v[234:235], v[242:243]
	v_pk_mul_f32 v[236:237], v[236:237], v[242:243]
	v_pk_mul_f32 v[238:239], v[238:239], v[242:243]
	v_exp_f32_e32 v232, v232
	v_exp_f32_e32 v233, v233
	v_exp_f32_e32 v234, v234
	v_exp_f32_e32 v235, v235
	v_exp_f32_e32 v236, v236
	v_exp_f32_e32 v237, v237
	v_exp_f32_e32 v238, v238
	v_exp_f32_e32 v239, v239
	v_pk_add_f32 v[232:233], v[232:233], v[244:245]
	v_pk_add_f32 v[234:235], v[234:235], v[244:245]
	v_pk_add_f32 v[236:237], v[236:237], v[244:245]
	v_pk_add_f32 v[238:239], v[238:239], v[244:245]
	v_rcp_f32_e32 v232, v232
	v_rcp_f32_e32 v233, v233
	v_rcp_f32_e32 v234, v234
	v_rcp_f32_e32 v235, v235
	v_rcp_f32_e32 v236, v236
	v_rcp_f32_e32 v237, v237
; __device__ __forceinline__ unsigned cvt_pk_bf16(float lo, float hi) { unsigned r; asm volatile("v_cvt_pk_bf16_f32 %0, %1, %2" : "=v"(r) : "v"(lo), "v"(hi)); return r; }
; __device__ __forceinline__ float gelu_tanh(float x) {
;     const float t = x * (1.0f + 0.044715f * x * x);
;     const float e = __builtin_amdgcn_exp2f(-2.0f * 0.7978845608028654f * 1.4426950408889634f * t);
;     return x * __builtin_amdgcn_rcpf(1.0f + e);
; }
;     __device__ __forceinline__ void operator()(const f32x4 (&acc)[2][2][4][2], const Unit& u, int wr, int wc, int fr, int fq) const {
;     ...
;             const int col0 = u.pn * BM + wc * 32 + 8 * fq;
; #pragma unroll
;             for (int ai = 0; ai < 2; ++ai)
; #pragma unroll
;                 for (int m = 0; m < 4; ++m) { bf16_t* rowp = Zo + (size_t)(row0 + ai * HALF + m * 16) * NZ + col0;
; #pragma unroll
;                     for (int bj = 0; bj < 2; ++bj) { f32x4 v0 = acc[ai][bj][m][0], v1 = acc[ai][bj][m][1];
; #pragma unroll
;                         for (int e = 0; e < 4; ++e) { v0[e] = gelu_tanh(v0[e]); v1[e] = gelu_tanh(v1[e]); }
;                         u32x4 w; w.x = cvt_pk_bf16(v0[0], v0[1]); w.y = cvt_pk_bf16(v0[2], v0[3]); w.z = cvt_pk_bf16(v1[0], v1[1]); w.w = cvt_pk_bf16(v1[2], v1[3]);
;                         *(u32x4*)(rowp + bj * HALF) = w; } }
	v_rcp_f32_e32 v238, v238
	v_rcp_f32_e32 v239, v239
	v_pk_mul_f32 v[232:233], v[84:85], v[232:233]
	v_pk_mul_f32 v[234:235], v[86:87], v[234:235]
	v_pk_mul_f32 v[236:237], v[80:81], v[236:237]
	v_pk_mul_f32 v[238:239], v[82:83], v[238:239]
	v_cvt_pk_bf16_f32 v246, v232, v233
	v_cvt_pk_bf16_f32 v247, v234, v235
	v_cvt_pk_bf16_f32 v248, v236, v237
	v_cvt_pk_bf16_f32 v249, v238, v239
	global_store_dwordx4 v[250:251], v[246:249], off offset:256
	v_or_b32_e32 v250, 48, v160
	v_mad_i64_i32 v[250:251], s[8:9], v250, s69, v[158:159]
	v_lshl_add_u64 v[250:251], v[250:251], 0, v[136:137]
	v_pk_mul_f32 v[232:233], v[76:77], v[240:241]
	v_pk_mul_f32 v[234:235], v[78:79], v[240:241]
	v_pk_mul_f32 v[236:237], v[72:73], v[240:241]
	v_pk_mul_f32 v[238:239], v[74:75], v[240:241]
	v_pk_fma_f32 v[232:233], v[76:77], v[232:233], v[244:245]
	v_pk_fma_f32 v[234:235], v[78:79], v[234:235], v[244:245]
	v_pk_fma_f32 v[236:237], v[72:73], v[236:237], v[244:245]
	v_pk_fma_f32 v[238:239], v[74:75], v[238:239], v[244:245]
	v_pk_mul_f32 v[232:233], v[76:77], v[232:233]
	v_pk_mul_f32 v[234:235], v[78:79], v[234:235]
	v_pk_mul_f32 v[236:237], v[72:73], v[236:237]
	v_pk_mul_f32 v[238:239], v[74:75], v[238:239]
	v_pk_mul_f32 v[232:233], v[232:233], v[242:243]
	v_pk_mul_f32 v[234:235], v[234:235], v[242:243]
	v_pk_mul_f32 v[236:237], v[236:237], v[242:243]
	v_pk_mul_f32 v[238:239], v[238:239], v[242:243]
	v_exp_f32_e32 v232, v232
	v_exp_f32_e32 v233, v233
	v_exp_f32_e32 v234, v234
	v_exp_f32_e32 v235, v235
	v_exp_f32_e32 v236, v236
	v_exp_f32_e32 v237, v237
	v_exp_f32_e32 v238, v238
	v_exp_f32_e32 v239, v239
	v_pk_add_f32 v[232:233], v[232:233], v[244:245]
	v_pk_add_f32 v[234:235], v[234:235], v[244:245]
	v_pk_add_f32 v[236:237], v[236:237], v[244:245]
	v_pk_add_f32 v[238:239], v[238:239], v[244:245]
	v_rcp_f32_e32 v232, v232
	v_rcp_f32_e32 v233, v233
	v_rcp_f32_e32 v234, v234
	v_rcp_f32_e32 v235, v235
	v_rcp_f32_e32 v236, v236
	v_rcp_f32_e32 v237, v237
	v_rcp_f32_e32 v238, v238
	v_rcp_f32_e32 v239, v239
	v_pk_mul_f32 v[232:233], v[76:77], v[232:233]
	v_pk_mul_f32 v[234:235], v[78:79], v[234:235]
	v_pk_mul_f32 v[236:237], v[72:73], v[236:237]
	v_pk_mul_f32 v[238:239], v[74:75], v[238:239]
	v_cvt_pk_bf16_f32 v246, v232, v233
	v_cvt_pk_bf16_f32 v247, v234, v235
	v_cvt_pk_bf16_f32 v248, v236, v237
	v_cvt_pk_bf16_f32 v249, v238, v239
	global_store_dwordx4 v[250:251], v[246:249], off
	s_nop 1
	v_pk_mul_f32 v[232:233], v[68:69], v[240:241]
	v_pk_mul_f32 v[234:235], v[70:71], v[240:241]
	v_pk_mul_f32 v[236:237], v[64:65], v[240:241]
	v_pk_mul_f32 v[238:239], v[66:67], v[240:241]
	v_pk_fma_f32 v[232:233], v[68:69], v[232:233], v[244:245]
	v_pk_fma_f32 v[234:235], v[70:71], v[234:235], v[244:245]
	v_pk_fma_f32 v[236:237], v[64:65], v[236:237], v[244:245]
	v_pk_fma_f32 v[238:239], v[66:67], v[238:239], v[244:245]
	v_pk_mul_f32 v[232:233], v[68:69], v[232:233]
	v_pk_mul_f32 v[234:235], v[70:71], v[234:235]
	v_pk_mul_f32 v[236:237], v[64:65], v[236:237]
	v_pk_mul_f32 v[238:239], v[66:67], v[238:239]
	v_pk_mul_f32 v[232:233], v[232:233], v[242:243]
	v_pk_mul_f32 v[234:235], v[234:235], v[242:243]
	v_pk_mul_f32 v[236:237], v[236:237], v[242:243]
	v_pk_mul_f32 v[238:239], v[238:239], v[242:243]
	v_exp_f32_e32 v232, v232
	v_exp_f32_e32 v233, v233
	v_exp_f32_e32 v234, v234
	v_exp_f32_e32 v235, v235
	v_exp_f32_e32 v236, v236
	v_exp_f32_e32 v237, v237
	v_exp_f32_e32 v238, v238
	v_exp_f32_e32 v239, v239
	v_pk_add_f32 v[232:233], v[232:233], v[244:245]
	v_pk_add_f32 v[234:235], v[234:235], v[244:245]
	v_pk_add_f32 v[236:237], v[236:237], v[244:245]
	v_pk_add_f32 v[238:239], v[238:239], v[244:245]
	v_rcp_f32_e32 v232, v232
	v_rcp_f32_e32 v233, v233
	v_rcp_f32_e32 v234, v234
	v_rcp_f32_e32 v235, v235
	v_rcp_f32_e32 v236, v236
	v_rcp_f32_e32 v237, v237
	v_rcp_f32_e32 v238, v238
	v_rcp_f32_e32 v239, v239
	v_pk_mul_f32 v[232:233], v[68:69], v[232:233]
	v_pk_mul_f32 v[234:235], v[70:71], v[234:235]
	v_pk_mul_f32 v[236:237], v[64:65], v[236:237]
	v_pk_mul_f32 v[238:239], v[66:67], v[238:239]
	v_cvt_pk_bf16_f32 v246, v232, v233
	v_cvt_pk_bf16_f32 v247, v234, v235
	v_cvt_pk_bf16_f32 v248, v236, v237
	v_cvt_pk_bf16_f32 v249, v238, v239
	global_store_dwordx4 v[250:251], v[246:249], off offset:256
	v_add_u32_e32 v250, 0x80, v160
	v_mad_i64_i32 v[250:251], s[8:9], v250, s69, v[158:159]
	v_lshl_add_u64 v[250:251], v[250:251], 0, v[136:137]
	v_pk_mul_f32 v[232:233], v[60:61], v[240:241]
	v_pk_mul_f32 v[234:235], v[62:63], v[240:241]
	v_pk_mul_f32 v[236:237], v[56:57], v[240:241]
	v_pk_mul_f32 v[238:239], v[58:59], v[240:241]
	v_pk_fma_f32 v[232:233], v[60:61], v[232:233], v[244:245]
	v_pk_fma_f32 v[234:235], v[62:63], v[234:235], v[244:245]
	v_pk_fma_f32 v[236:237], v[56:57], v[236:237], v[244:245]
	v_pk_fma_f32 v[238:239], v[58:59], v[238:239], v[244:245]
	v_pk_mul_f32 v[232:233], v[60:61], v[232:233]
	v_pk_mul_f32 v[234:235], v[62:63], v[234:235]
	v_pk_mul_f32 v[236:237], v[56:57], v[236:237]
	v_pk_mul_f32 v[238:239], v[58:59], v[238:239]
	v_pk_mul_f32 v[232:233], v[232:233], v[242:243]
	v_pk_mul_f32 v[234:235], v[234:235], v[242:243]
	v_pk_mul_f32 v[236:237], v[236:237], v[242:243]
	v_pk_mul_f32 v[238:239], v[238:239], v[242:243]
	v_exp_f32_e32 v232, v232
	v_exp_f32_e32 v233, v233
	v_exp_f32_e32 v234, v234
	v_exp_f32_e32 v235, v235
	v_exp_f32_e32 v236, v236
	v_exp_f32_e32 v237, v237
	v_exp_f32_e32 v238, v238
	v_exp_f32_e32 v239, v239
	v_pk_add_f32 v[232:233], v[232:233], v[244:245]
	v_pk_add_f32 v[234:235], v[234:235], v[244:245]
	v_pk_add_f32 v[236:237], v[236:237], v[244:245]
	v_pk_add_f32 v[238:239], v[238:239], v[244:245]
	v_rcp_f32_e32 v232, v232
	v_rcp_f32_e32 v233, v233
	v_rcp_f32_e32 v234, v234
; __device__ __forceinline__ unsigned cvt_pk_bf16(float lo, float hi) { unsigned r; asm volatile("v_cvt_pk_bf16_f32 %0, %1, %2" : "=v"(r) : "v"(lo), "v"(hi)); return r; }
; __device__ __forceinline__ float gelu_tanh(float x) {
;     const float t = x * (1.0f + 0.044715f * x * x);
;     const float e = __builtin_amdgcn_exp2f(-2.0f * 0.7978845608028654f * 1.4426950408889634f * t);
;     return x * __builtin_amdgcn_rcpf(1.0f + e);
; }
;     __device__ __forceinline__ void operator()(const f32x4 (&acc)[2][2][4][2], const Unit& u, int wr, int wc, int fr, int fq) const {
;     ...
;             const int col0 = u.pn * BM + wc * 32 + 8 * fq;
; #pragma unroll
;             for (int ai = 0; ai < 2; ++ai)
; #pragma unroll
;                 for (int m = 0; m < 4; ++m) { bf16_t* rowp = Zo + (size_t)(row0 + ai * HALF + m * 16) * NZ + col0;
; #pragma unroll
;                     for (int bj = 0; bj < 2; ++bj) { f32x4 v0 = acc[ai][bj][m][0], v1 = acc[ai][bj][m][1];
; #pragma unroll
;                         for (int e = 0; e < 4; ++e) { v0[e] = gelu_tanh(v0[e]); v1[e] = gelu_tanh(v1[e]); }
;                         u32x4 w; w.x = cvt_pk_bf16(v0[0], v0[1]); w.y = cvt_pk_bf16(v0[2], v0[3]); w.z = cvt_pk_bf16(v1[0], v1[1]); w.w = cvt_pk_bf16(v1[2], v1[3]);
;                         *(u32x4*)(rowp + bj * HALF) = w; } }
	v_rcp_f32_e32 v235, v235
	v_rcp_f32_e32 v236, v236
	v_rcp_f32_e32 v237, v237
	v_rcp_f32_e32 v238, v238
	v_rcp_f32_e32 v239, v239
	v_pk_mul_f32 v[232:233], v[60:61], v[232:233]
	v_pk_mul_f32 v[234:235], v[62:63], v[234:235]
	v_pk_mul_f32 v[236:237], v[56:57], v[236:237]
	v_pk_mul_f32 v[238:239], v[58:59], v[238:239]
	v_cvt_pk_bf16_f32 v246, v232, v233
	v_cvt_pk_bf16_f32 v247, v234, v235
	v_cvt_pk_bf16_f32 v248, v236, v237
	v_cvt_pk_bf16_f32 v249, v238, v239
	global_store_dwordx4 v[250:251], v[246:249], off
	s_nop 1
	v_pk_mul_f32 v[232:233], v[52:53], v[240:241]
	v_pk_mul_f32 v[234:235], v[54:55], v[240:241]
	v_pk_mul_f32 v[236:237], v[48:49], v[240:241]
	v_pk_mul_f32 v[238:239], v[50:51], v[240:241]
	v_pk_fma_f32 v[232:233], v[52:53], v[232:233], v[244:245]
	v_pk_fma_f32 v[234:235], v[54:55], v[234:235], v[244:245]
	v_pk_fma_f32 v[236:237], v[48:49], v[236:237], v[244:245]
	v_pk_fma_f32 v[238:239], v[50:51], v[238:239], v[244:245]
	v_pk_mul_f32 v[232:233], v[52:53], v[232:233]
	v_pk_mul_f32 v[234:235], v[54:55], v[234:235]
	v_pk_mul_f32 v[236:237], v[48:49], v[236:237]
	v_pk_mul_f32 v[238:239], v[50:51], v[238:239]
	v_pk_mul_f32 v[232:233], v[232:233], v[242:243]
	v_pk_mul_f32 v[234:235], v[234:235], v[242:243]
	v_pk_mul_f32 v[236:237], v[236:237], v[242:243]
	v_pk_mul_f32 v[238:239], v[238:239], v[242:243]
	v_exp_f32_e32 v232, v232
	v_exp_f32_e32 v233, v233
	v_exp_f32_e32 v234, v234
	v_exp_f32_e32 v235, v235
	v_exp_f32_e32 v236, v236
	v_exp_f32_e32 v237, v237
	v_exp_f32_e32 v238, v238
	v_exp_f32_e32 v239, v239
	v_pk_add_f32 v[232:233], v[232:233], v[244:245]
	v_pk_add_f32 v[234:235], v[234:235], v[244:245]
	v_pk_add_f32 v[236:237], v[236:237], v[244:245]
	v_pk_add_f32 v[238:239], v[238:239], v[244:245]
	v_rcp_f32_e32 v232, v232
	v_rcp_f32_e32 v233, v233
	v_rcp_f32_e32 v234, v234
	v_rcp_f32_e32 v235, v235
	v_rcp_f32_e32 v236, v236
	v_rcp_f32_e32 v237, v237
	v_rcp_f32_e32 v238, v238
	v_rcp_f32_e32 v239, v239
	v_pk_mul_f32 v[232:233], v[52:53], v[232:233]
	v_pk_mul_f32 v[234:235], v[54:55], v[234:235]
	v_pk_mul_f32 v[236:237], v[48:49], v[236:237]
	v_pk_mul_f32 v[238:239], v[50:51], v[238:239]
	v_cvt_pk_bf16_f32 v246, v232, v233
	v_cvt_pk_bf16_f32 v247, v234, v235
	v_cvt_pk_bf16_f32 v248, v236, v237
	v_cvt_pk_bf16_f32 v249, v238, v239
	global_store_dwordx4 v[250:251], v[246:249], off offset:256
	v_add_u32_e32 v250, 0x90, v160
	v_mad_i64_i32 v[250:251], s[8:9], v250, s69, v[158:159]
	v_lshl_add_u64 v[250:251], v[250:251], 0, v[136:137]
	v_pk_mul_f32 v[232:233], v[44:45], v[240:241]
	v_pk_mul_f32 v[234:235], v[46:47], v[240:241]
	v_pk_mul_f32 v[236:237], v[40:41], v[240:241]
	v_pk_mul_f32 v[238:239], v[42:43], v[240:241]
	v_pk_fma_f32 v[232:233], v[44:45], v[232:233], v[244:245]
	v_pk_fma_f32 v[234:235], v[46:47], v[234:235], v[244:245]
	v_pk_fma_f32 v[236:237], v[40:41], v[236:237], v[244:245]
	v_pk_fma_f32 v[238:239], v[42:43], v[238:239], v[244:245]
	v_pk_mul_f32 v[232:233], v[44:45], v[232:233]
	v_pk_mul_f32 v[234:235], v[46:47], v[234:235]
	v_pk_mul_f32 v[236:237], v[40:41], v[236:237]
	v_pk_mul_f32 v[238:239], v[42:43], v[238:239]
	v_pk_mul_f32 v[232:233], v[232:233], v[242:243]
	v_pk_mul_f32 v[234:235], v[234:235], v[242:243]
	v_pk_mul_f32 v[236:237], v[236:237], v[242:243]
	v_pk_mul_f32 v[238:239], v[238:239], v[242:243]
	v_exp_f32_e32 v232, v232
	v_exp_f32_e32 v233, v233
	v_exp_f32_e32 v234, v234
	v_exp_f32_e32 v235, v235
	v_exp_f32_e32 v236, v236
	v_exp_f32_e32 v237, v237
	v_exp_f32_e32 v238, v238
	v_exp_f32_e32 v239, v239
	v_pk_add_f32 v[232:233], v[232:233], v[244:245]
	v_pk_add_f32 v[234:235], v[234:235], v[244:245]
	v_pk_add_f32 v[236:237], v[236:237], v[244:245]
	v_pk_add_f32 v[238:239], v[238:239], v[244:245]
	v_rcp_f32_e32 v232, v232
	v_rcp_f32_e32 v233, v233
	v_rcp_f32_e32 v234, v234
	v_rcp_f32_e32 v235, v235
	v_rcp_f32_e32 v236, v236
	v_rcp_f32_e32 v237, v237
	v_rcp_f32_e32 v238, v238
	v_rcp_f32_e32 v239, v239
	v_pk_mul_f32 v[232:233], v[44:45], v[232:233]
	v_pk_mul_f32 v[234:235], v[46:47], v[234:235]
	v_pk_mul_f32 v[236:237], v[40:41], v[236:237]
	v_pk_mul_f32 v[238:239], v[42:43], v[238:239]
	v_cvt_pk_bf16_f32 v246, v232, v233
	v_cvt_pk_bf16_f32 v247, v234, v235
	v_cvt_pk_bf16_f32 v248, v236, v237
	v_cvt_pk_bf16_f32 v249, v238, v239
	global_store_dwordx4 v[250:251], v[246:249], off
	s_nop 1
	v_pk_mul_f32 v[232:233], v[36:37], v[240:241]
	v_pk_mul_f32 v[234:235], v[38:39], v[240:241]
	v_pk_mul_f32 v[236:237], v[32:33], v[240:241]
	v_pk_mul_f32 v[238:239], v[34:35], v[240:241]
	v_pk_fma_f32 v[232:233], v[36:37], v[232:233], v[244:245]
	v_pk_fma_f32 v[234:235], v[38:39], v[234:235], v[244:245]
	v_pk_fma_f32 v[236:237], v[32:33], v[236:237], v[244:245]
	v_pk_fma_f32 v[238:239], v[34:35], v[238:239], v[244:245]
	v_pk_mul_f32 v[232:233], v[36:37], v[232:233]
	v_pk_mul_f32 v[234:235], v[38:39], v[234:235]
	v_pk_mul_f32 v[236:237], v[32:33], v[236:237]
	v_pk_mul_f32 v[238:239], v[34:35], v[238:239]
	v_pk_mul_f32 v[232:233], v[232:233], v[242:243]
	v_pk_mul_f32 v[234:235], v[234:235], v[242:243]
	v_pk_mul_f32 v[236:237], v[236:237], v[242:243]
	v_pk_mul_f32 v[238:239], v[238:239], v[242:243]
	v_exp_f32_e32 v232, v232
	v_exp_f32_e32 v233, v233
	v_exp_f32_e32 v234, v234
	v_exp_f32_e32 v235, v235
	v_exp_f32_e32 v236, v236
	v_exp_f32_e32 v237, v237
	v_exp_f32_e32 v238, v238
	v_exp_f32_e32 v239, v239
	v_pk_add_f32 v[232:233], v[232:233], v[244:245]
	v_pk_add_f32 v[234:235], v[234:235], v[244:245]
	v_pk_add_f32 v[236:237], v[236:237], v[244:245]
	v_pk_add_f32 v[238:239], v[238:239], v[244:245]
	v_rcp_f32_e32 v232, v232
	v_rcp_f32_e32 v233, v233
	v_rcp_f32_e32 v234, v234
	v_rcp_f32_e32 v235, v235
	v_rcp_f32_e32 v236, v236
; __device__ __forceinline__ unsigned cvt_pk_bf16(float lo, float hi) { unsigned r; asm volatile("v_cvt_pk_bf16_f32 %0, %1, %2" : "=v"(r) : "v"(lo), "v"(hi)); return r; }
; __device__ __forceinline__ float gelu_tanh(float x) {
;     const float t = x * (1.0f + 0.044715f * x * x);
;     const float e = __builtin_amdgcn_exp2f(-2.0f * 0.7978845608028654f * 1.4426950408889634f * t);
;     return x * __builtin_amdgcn_rcpf(1.0f + e);
; }
;     __device__ __forceinline__ void operator()(const f32x4 (&acc)[2][2][4][2], const Unit& u, int wr, int wc, int fr, int fq) const {
;     ...
;             const int col0 = u.pn * BM + wc * 32 + 8 * fq;
; #pragma unroll
;             for (int ai = 0; ai < 2; ++ai)
; #pragma unroll
;                 for (int m = 0; m < 4; ++m) { bf16_t* rowp = Zo + (size_t)(row0 + ai * HALF + m * 16) * NZ + col0;
; #pragma unroll
;                     for (int bj = 0; bj < 2; ++bj) { f32x4 v0 = acc[ai][bj][m][0], v1 = acc[ai][bj][m][1];
; #pragma unroll
;                         for (int e = 0; e < 4; ++e) { v0[e] = gelu_tanh(v0[e]); v1[e] = gelu_tanh(v1[e]); }
;                         u32x4 w; w.x = cvt_pk_bf16(v0[0], v0[1]); w.y = cvt_pk_bf16(v0[2], v0[3]); w.z = cvt_pk_bf16(v1[0], v1[1]); w.w = cvt_pk_bf16(v1[2], v1[3]);
;                         *(u32x4*)(rowp + bj * HALF) = w; } }
	v_rcp_f32_e32 v237, v237
	v_rcp_f32_e32 v238, v238
	v_rcp_f32_e32 v239, v239
	v_pk_mul_f32 v[232:233], v[36:37], v[232:233]
	v_pk_mul_f32 v[234:235], v[38:39], v[234:235]
	v_pk_mul_f32 v[236:237], v[32:33], v[236:237]
	v_pk_mul_f32 v[238:239], v[34:35], v[238:239]
	v_cvt_pk_bf16_f32 v246, v232, v233
	v_cvt_pk_bf16_f32 v247, v234, v235
	v_cvt_pk_bf16_f32 v248, v236, v237
	v_cvt_pk_bf16_f32 v249, v238, v239
	global_store_dwordx4 v[250:251], v[246:249], off offset:256
	v_add_u32_e32 v250, 0xa0, v160
	v_mad_i64_i32 v[250:251], s[8:9], v250, s69, v[158:159]
	v_lshl_add_u64 v[250:251], v[250:251], 0, v[136:137]
	v_pk_mul_f32 v[232:233], v[28:29], v[240:241]
	v_pk_mul_f32 v[234:235], v[30:31], v[240:241]
	v_pk_mul_f32 v[236:237], v[24:25], v[240:241]
	v_pk_mul_f32 v[238:239], v[26:27], v[240:241]
	v_pk_fma_f32 v[232:233], v[28:29], v[232:233], v[244:245]
	v_pk_fma_f32 v[234:235], v[30:31], v[234:235], v[244:245]
	v_pk_fma_f32 v[236:237], v[24:25], v[236:237], v[244:245]
	v_pk_fma_f32 v[238:239], v[26:27], v[238:239], v[244:245]
	v_pk_mul_f32 v[232:233], v[28:29], v[232:233]
	v_pk_mul_f32 v[234:235], v[30:31], v[234:235]
	v_pk_mul_f32 v[236:237], v[24:25], v[236:237]
	v_pk_mul_f32 v[238:239], v[26:27], v[238:239]
	v_pk_mul_f32 v[232:233], v[232:233], v[242:243]
	v_pk_mul_f32 v[234:235], v[234:235], v[242:243]
	v_pk_mul_f32 v[236:237], v[236:237], v[242:243]
	v_pk_mul_f32 v[238:239], v[238:239], v[242:243]
	v_exp_f32_e32 v232, v232
	v_exp_f32_e32 v233, v233
	v_exp_f32_e32 v234, v234
	v_exp_f32_e32 v235, v235
	v_exp_f32_e32 v236, v236
	v_exp_f32_e32 v237, v237
	v_exp_f32_e32 v238, v238
	v_exp_f32_e32 v239, v239
	v_pk_add_f32 v[232:233], v[232:233], v[244:245]
	v_pk_add_f32 v[234:235], v[234:235], v[244:245]
	v_pk_add_f32 v[236:237], v[236:237], v[244:245]
	v_pk_add_f32 v[238:239], v[238:239], v[244:245]
	v_rcp_f32_e32 v232, v232
	v_rcp_f32_e32 v233, v233
	v_rcp_f32_e32 v234, v234
	v_rcp_f32_e32 v235, v235
	v_rcp_f32_e32 v236, v236
	v_rcp_f32_e32 v237, v237
	v_rcp_f32_e32 v238, v238
	v_rcp_f32_e32 v239, v239
	v_pk_mul_f32 v[232:233], v[28:29], v[232:233]
	v_pk_mul_f32 v[234:235], v[30:31], v[234:235]
	v_pk_mul_f32 v[236:237], v[24:25], v[236:237]
	v_pk_mul_f32 v[238:239], v[26:27], v[238:239]
	v_cvt_pk_bf16_f32 v246, v232, v233
	v_cvt_pk_bf16_f32 v247, v234, v235
	v_cvt_pk_bf16_f32 v248, v236, v237
	v_cvt_pk_bf16_f32 v249, v238, v239
	global_store_dwordx4 v[250:251], v[246:249], off
	s_nop 1
	v_pk_mul_f32 v[232:233], v[20:21], v[240:241]
	v_pk_mul_f32 v[234:235], v[22:23], v[240:241]
	v_pk_mul_f32 v[236:237], v[16:17], v[240:241]
	v_pk_mul_f32 v[238:239], v[18:19], v[240:241]
	v_pk_fma_f32 v[232:233], v[20:21], v[232:233], v[244:245]
	v_pk_fma_f32 v[234:235], v[22:23], v[234:235], v[244:245]
	v_pk_fma_f32 v[236:237], v[16:17], v[236:237], v[244:245]
	v_pk_fma_f32 v[238:239], v[18:19], v[238:239], v[244:245]
	v_pk_mul_f32 v[232:233], v[20:21], v[232:233]
	v_pk_mul_f32 v[234:235], v[22:23], v[234:235]
	v_pk_mul_f32 v[236:237], v[16:17], v[236:237]
	v_pk_mul_f32 v[238:239], v[18:19], v[238:239]
	v_pk_mul_f32 v[232:233], v[232:233], v[242:243]
	v_pk_mul_f32 v[234:235], v[234:235], v[242:243]
	v_pk_mul_f32 v[236:237], v[236:237], v[242:243]
	v_pk_mul_f32 v[238:239], v[238:239], v[242:243]
	v_exp_f32_e32 v232, v232
	v_exp_f32_e32 v233, v233
	v_exp_f32_e32 v234, v234
	v_exp_f32_e32 v235, v235
	v_exp_f32_e32 v236, v236
	v_exp_f32_e32 v237, v237
	v_exp_f32_e32 v238, v238
	v_exp_f32_e32 v239, v239
	v_pk_add_f32 v[232:233], v[232:233], v[244:245]
	v_pk_add_f32 v[234:235], v[234:235], v[244:245]
	v_pk_add_f32 v[236:237], v[236:237], v[244:245]
	v_pk_add_f32 v[238:239], v[238:239], v[244:245]
	v_rcp_f32_e32 v232, v232
	v_rcp_f32_e32 v233, v233
	v_rcp_f32_e32 v234, v234
	v_rcp_f32_e32 v235, v235
	v_rcp_f32_e32 v236, v236
	v_rcp_f32_e32 v237, v237
	v_rcp_f32_e32 v238, v238
	v_rcp_f32_e32 v239, v239
	v_pk_mul_f32 v[232:233], v[20:21], v[232:233]
	v_pk_mul_f32 v[234:235], v[22:23], v[234:235]
	v_pk_mul_f32 v[236:237], v[16:17], v[236:237]
	v_pk_mul_f32 v[238:239], v[18:19], v[238:239]
; __device__ __forceinline__ unsigned cvt_pk_bf16(float lo, float hi) { unsigned r; asm volatile("v_cvt_pk_bf16_f32 %0, %1, %2" : "=v"(r) : "v"(lo), "v"(hi)); return r; }
; __device__ __forceinline__ float gelu_tanh(float x) {
;     const float t = x * (1.0f + 0.044715f * x * x);
;     const float e = __builtin_amdgcn_exp2f(-2.0f * 0.7978845608028654f * 1.4426950408889634f * t);
;     return x * __builtin_amdgcn_rcpf(1.0f + e);
; }
;     __device__ __forceinline__ void operator()(const f32x4 (&acc)[2][2][4][2], const Unit& u, int wr, int wc, int fr, int fq) const {
;     ...
;             const int col0 = u.pn * BM + wc * 32 + 8 * fq;
; #pragma unroll
;             for (int ai = 0; ai < 2; ++ai)
; #pragma unroll
;                 for (int m = 0; m < 4; ++m) { bf16_t* rowp = Zo + (size_t)(row0 + ai * HALF + m * 16) * NZ + col0;
; #pragma unroll
;                     for (int bj = 0; bj < 2; ++bj) { f32x4 v0 = acc[ai][bj][m][0], v1 = acc[ai][bj][m][1];
; #pragma unroll
;                         for (int e = 0; e < 4; ++e) { v0[e] = gelu_tanh(v0[e]); v1[e] = gelu_tanh(v1[e]); }
;                         u32x4 w; w.x = cvt_pk_bf16(v0[0], v0[1]); w.y = cvt_pk_bf16(v0[2], v0[3]); w.z = cvt_pk_bf16(v1[0], v1[1]); w.w = cvt_pk_bf16(v1[2], v1[3]);
;                         *(u32x4*)(rowp + bj * HALF) = w; } }
	v_cvt_pk_bf16_f32 v246, v232, v233
	v_cvt_pk_bf16_f32 v247, v234, v235
	v_cvt_pk_bf16_f32 v248, v236, v237
	v_cvt_pk_bf16_f32 v249, v238, v239
	global_store_dwordx4 v[250:251], v[246:249], off offset:256
	v_add_u32_e32 v250, 0xb0, v160
	v_mad_i64_i32 v[250:251], s[8:9], v250, s69, v[158:159]
	v_lshl_add_u64 v[250:251], v[250:251], 0, v[136:137]
	v_pk_mul_f32 v[232:233], v[12:13], v[240:241]
	v_pk_mul_f32 v[234:235], v[14:15], v[240:241]
	v_pk_mul_f32 v[236:237], v[8:9], v[240:241]
	v_pk_mul_f32 v[238:239], v[10:11], v[240:241]
	v_pk_fma_f32 v[232:233], v[12:13], v[232:233], v[244:245]
	v_pk_fma_f32 v[234:235], v[14:15], v[234:235], v[244:245]
	v_pk_fma_f32 v[236:237], v[8:9], v[236:237], v[244:245]
	v_pk_fma_f32 v[238:239], v[10:11], v[238:239], v[244:245]
	v_pk_mul_f32 v[232:233], v[12:13], v[232:233]
	v_pk_mul_f32 v[234:235], v[14:15], v[234:235]
	v_pk_mul_f32 v[236:237], v[8:9], v[236:237]
	v_pk_mul_f32 v[238:239], v[10:11], v[238:239]
	v_pk_mul_f32 v[232:233], v[232:233], v[242:243]
	v_pk_mul_f32 v[234:235], v[234:235], v[242:243]
	v_pk_mul_f32 v[236:237], v[236:237], v[242:243]
	v_pk_mul_f32 v[238:239], v[238:239], v[242:243]
	v_exp_f32_e32 v232, v232
	v_exp_f32_e32 v233, v233
	v_exp_f32_e32 v234, v234
	v_exp_f32_e32 v235, v235
	v_exp_f32_e32 v236, v236
	v_exp_f32_e32 v237, v237
	v_exp_f32_e32 v238, v238
	v_exp_f32_e32 v239, v239
	v_pk_add_f32 v[232:233], v[232:233], v[244:245]
	v_pk_add_f32 v[234:235], v[234:235], v[244:245]
	v_pk_add_f32 v[236:237], v[236:237], v[244:245]
	v_pk_add_f32 v[238:239], v[238:239], v[244:245]
	v_rcp_f32_e32 v232, v232
	v_rcp_f32_e32 v233, v233
	v_rcp_f32_e32 v234, v234
	v_rcp_f32_e32 v235, v235
	v_rcp_f32_e32 v236, v236
	v_rcp_f32_e32 v237, v237
	v_rcp_f32_e32 v238, v238
	v_rcp_f32_e32 v239, v239
	v_pk_mul_f32 v[232:233], v[12:13], v[232:233]
	v_pk_mul_f32 v[234:235], v[14:15], v[234:235]
	v_pk_mul_f32 v[236:237], v[8:9], v[236:237]
	v_pk_mul_f32 v[238:239], v[10:11], v[238:239]
	v_cvt_pk_bf16_f32 v246, v232, v233
	v_cvt_pk_bf16_f32 v247, v234, v235
	v_cvt_pk_bf16_f32 v248, v236, v237
	v_cvt_pk_bf16_f32 v249, v238, v239
	global_store_dwordx4 v[250:251], v[246:249], off
	s_nop 1
	v_pk_mul_f32 v[232:233], v[4:5], v[240:241]
	v_pk_mul_f32 v[234:235], v[6:7], v[240:241]
	v_pk_mul_f32 v[236:237], v[0:1], v[240:241]
	v_pk_mul_f32 v[238:239], v[2:3], v[240:241]
	v_pk_fma_f32 v[232:233], v[4:5], v[232:233], v[244:245]
	v_pk_fma_f32 v[234:235], v[6:7], v[234:235], v[244:245]
	v_pk_fma_f32 v[236:237], v[0:1], v[236:237], v[244:245]
	v_pk_fma_f32 v[238:239], v[2:3], v[238:239], v[244:245]
	v_pk_mul_f32 v[232:233], v[4:5], v[232:233]
	v_pk_mul_f32 v[234:235], v[6:7], v[234:235]
	v_pk_mul_f32 v[236:237], v[0:1], v[236:237]
	v_pk_mul_f32 v[238:239], v[2:3], v[238:239]
	v_pk_mul_f32 v[232:233], v[232:233], v[242:243]
	v_pk_mul_f32 v[234:235], v[234:235], v[242:243]
	v_pk_mul_f32 v[236:237], v[236:237], v[242:243]
	v_pk_mul_f32 v[238:239], v[238:239], v[242:243]
	v_exp_f32_e32 v232, v232
	v_exp_f32_e32 v233, v233
	v_exp_f32_e32 v234, v234
	v_exp_f32_e32 v235, v235
	v_exp_f32_e32 v236, v236
	v_exp_f32_e32 v237, v237
	v_exp_f32_e32 v238, v238
	v_exp_f32_e32 v239, v239
	v_pk_add_f32 v[232:233], v[232:233], v[244:245]
	v_pk_add_f32 v[234:235], v[234:235], v[244:245]
	v_pk_add_f32 v[236:237], v[236:237], v[244:245]
	v_pk_add_f32 v[238:239], v[238:239], v[244:245]
	v_rcp_f32_e32 v232, v232
	v_rcp_f32_e32 v233, v233
	v_rcp_f32_e32 v234, v234
	v_rcp_f32_e32 v235, v235
	v_rcp_f32_e32 v236, v236
	v_rcp_f32_e32 v237, v237
	v_rcp_f32_e32 v238, v238
	v_rcp_f32_e32 v239, v239
	v_pk_mul_f32 v[232:233], v[4:5], v[232:233]
	v_pk_mul_f32 v[234:235], v[6:7], v[234:235]
	v_pk_mul_f32 v[236:237], v[0:1], v[236:237]
	v_pk_mul_f32 v[238:239], v[2:3], v[238:239]
	v_cvt_pk_bf16_f32 v246, v232, v233
	v_cvt_pk_bf16_f32 v247, v234, v235
	v_cvt_pk_bf16_f32 v248, v236, v237
	v_cvt_pk_bf16_f32 v249, v238, v239
	global_store_dwordx4 v[250:251], v[246:249], off offset:256
	s_andn2_b64 vcc, exec, s[6:7]
	s_mov_b64 s[6:7], -1
	s_cbranch_vccnz .LBB0_182
	s_branch .LBB0_274
